# weight conversion of everything but ada/W_up1(L0) moved from the prologue into the idle workgroups of the partial last GEMM rounds; ctx-query units balanced
# speedup vs baseline: 1.0118x; 1.0114x over previous
; #define LAS __attribute__((address_space(3)))
; __device__ __forceinline__ void prologue(const kptr_t kp, LAS float* scr, int gw, int NGW, int lane) {
;     unsigned char* ws = KPTR(unsigned char, 23);
;     for (int it = gw; it < IT_TOTAL; it += NGW) {
;         int r = it;
;         if (r < IT_ADA) {
;     ...
;         {
;             const int id = r * 64 + lane, pos = id >> 4, j = id & 15; const int p = pos < 256 ? pos : pos - 256;
;             const float freq = powf(10000.0f, -(float)j / 16.0f); const float ang = (float)p * freq;
;             float* t = (float*)(ws + CTL_ROPE) + (size_t)id * 2; t[0] = cosf(ang); t[1] = sinf(ang);
.LBB0_5:
	s_or_b64 exec, exec, s[4:5]
	s_load_dwordx2 s[100:101], s[0:1], 0xb8
	v_readfirstlane_b32 s99, v206
	s_ashr_i32 s99, s99, 6
	s_lshl_b32 s98, s2, 3
	s_add_i32 s99, s99, s98
	s_lshl_b32 s98, s99, 10
	v_and_b32_e32 v2, 63, v206
	v_lshlrev_b32_e32 v2, 4, v2
	v_add_u32_e32 v2, s98, v2
	v_mov_b32_e32 v4, 0
	v_mov_b32_e32 v5, 0
	v_mov_b32_e32 v6, 0
	v_mov_b32_e32 v7, 0
	s_waitcnt lgkmcnt(0)
	s_add_u32 s100, s100, 0x3120000
	s_addc_u32 s101, s101, 0
	s_cmp_lt_u32 s99, 896
	s_cbranch_scc0 .Lzero_skip
	global_store_dwordx4 v2, v[4:7], s[100:101]
.Lzero_skip:
	s_mov_b32 s98, 0
	s_movk_i32 s99, 0x800
	s_movk_i32 s100, 0xf80
	s_mov_b32 s101, 0
.Lcv_entry:
	s_mov_b64 s[36:37], s[0:1]
	v_mov_b32_e32 v1, v206
	s_lshl_b32 s33, s2, 3
	v_readfirstlane_b32 s3, v1
	s_ashr_i32 s4, s3, 6
	s_add_i32 s3, s4, s33
	s_add_i32 s3, s3, s98
	s_lshl_b32 s28, s30, 3
	s_cmp_ge_i32 s3, s100
	s_cbranch_scc1 .Lcv_ret
	v_and_b32_e32 v2, 15, v1
	v_cvt_f32_ubyte0_e32 v2, v2
	v_mul_f32_e32 v16, 0xbd800000, v2
	v_mov_b32_e32 v2, 0x461c4000
	v_cmp_eq_f32_e32 vcc, 0, v16
	s_lshl_b32 s4, s4, 14
	s_add_i32 s6, s4, 0
	v_cndmask_b32_e64 v12, v2, 1.0, vcc
	v_frexp_mant_f32_e32 v2, v12
	s_mov_b32 s4, 0x3f2aaaab
	v_cmp_gt_f32_e64 s[4:5], s4, v2
	s_movk_i32 s7, 0x204
	s_mov_b32 s9, 0x42b17218
	v_cndmask_b32_e64 v3, 1.0, 2.0, s[4:5]
	v_mul_f32_e32 v2, v2, v3
	v_add_f32_e32 v5, 1.0, v2
	v_rcp_f32_e32 v10, v5
	v_add_f32_e32 v3, -1.0, v5
	v_sub_f32_e32 v7, v2, v3
	v_add_f32_e32 v3, -1.0, v2
	v_mul_f32_e32 v11, v3, v10
	v_mul_f32_e32 v4, v5, v11
	v_fma_f32 v6, v11, v5, -v4
	v_fmac_f32_e32 v6, v11, v7
	v_add_f32_e32 v2, v4, v6
	v_sub_f32_e32 v5, v3, v2
	v_pk_add_f32 v[8:9], v[2:3], v[4:5] neg_lo:[0,1] neg_hi:[0,1]
	v_mov_b32_e32 v7, v2
	v_pk_add_f32 v[2:3], v[8:9], v[6:7] neg_lo:[0,1] neg_hi:[0,1]
	v_mov_b32_e32 v6, 0x3e91f4c4
	v_add_f32_e32 v2, v2, v3
	v_add_f32_e32 v2, v5, v2
	v_mul_f32_e32 v3, v10, v2
	v_add_f32_e32 v2, v11, v3
	v_sub_f32_e32 v4, v2, v11
	v_sub_f32_e32 v13, v3, v4
	v_mul_f32_e32 v3, v2, v2
	v_fma_f32 v5, v2, v2, -v3
	v_add_f32_e32 v4, v13, v13
	v_fmac_f32_e32 v5, v2, v4
	v_add_f32_e32 v4, v3, v5
	v_fmac_f32_e32 v6, 0x3e76c4e1, v4
	v_fmaak_f32 v6, v4, v6, 0x3ecccdef
	v_sub_f32_e32 v3, v4, v3
	v_sub_f32_e32 v14, v5, v3
	v_mul_f32_e32 v3, v4, v6
	v_fma_f32 v5, v4, v6, -v3
	v_fmac_f32_e32 v5, v14, v6
	v_add_f32_e32 v6, v3, v5
	v_add_f32_e32 v7, 0x3f2aaaaa, v6
	v_sub_f32_e32 v3, v6, v3
	v_sub_f32_e32 v3, v5, v3
	v_add_f32_e32 v5, 0xbf2aaaaa, v7
	v_add_f32_e32 v3, 0x31739010, v3
	v_sub_f32_e32 v5, v6, v5
	v_pk_mul_f32 v[8:9], v[2:3], v[4:5]
	v_pk_add_f32 v[10:11], v[2:3], v[4:5]
	v_fma_f32 v6, v4, v2, -v8
	v_fmac_f32_e32 v6, v4, v13
	v_mov_b32_e32 v9, v11
	v_fmac_f32_e32 v6, v14, v2
	v_pk_add_f32 v[4:5], v[8:9], v[6:7]
	v_ldexp_f32 v14, v13, 1
	v_sub_f32_e32 v3, v4, v8
	v_sub_f32_e32 v3, v6, v3
	v_sub_f32_e32 v6, v7, v5
	v_add_f32_e32 v9, v11, v6
	v_pk_mul_f32 v[6:7], v[4:5], v[4:5] op_sel:[0,1] op_sel_hi:[1,0]
	v_cvt_f64_f32_e32 v[10:11], v12
	v_frexp_exp_i32_f64_e32 v7, v[10:11]
	v_subbrev_co_u32_e64 v7, s[4:5], 0, v7, s[4:5]
	v_cvt_f32_i32_e32 v7, v7
	v_fma_f32 v8, v4, v5, -v6
	v_fmac_f32_e32 v8, v4, v9
	s_mov_b32 s4, 0x3f317218
	v_mul_f32_e32 v4, 0x3f317218, v7
	v_fmac_f32_e32 v8, v3, v5
	v_fma_f32 v3, v7, s4, -v4
	v_fmamk_f32 v10, v7, 0xb102e308, v3
	v_ldexp_f32 v11, v2, 1
	v_add_f32_e32 v5, v6, v8
	v_pk_add_f32 v[2:3], v[4:5], v[10:11]
	v_mov_b32_e32 v12, v5
	v_mov_b32_e32 v13, v3
	v_mov_b32_e32 v7, v11
	v_pk_add_f32 v[6:7], v[12:13], v[6:7] neg_lo:[0,1] neg_hi:[0,1]
	v_mov_b32_e32 v9, v5
	v_pk_add_f32 v[6:7], v[8:9], v[6:7] neg_lo:[0,1] neg_hi:[0,1]
	v_mov_b32_e32 v11, v2
	v_add_f32_e32 v5, v14, v6
	v_add_f32_e32 v5, v5, v7
	v_pk_add_f32 v[6:7], v[2:3], v[4:5] neg_lo:[0,1] neg_hi:[0,1]
	v_pk_add_f32 v[8:9], v[2:3], v[4:5]
	v_mov_b32_e32 v4, v5
	v_mov_b32_e32 v7, v9
	v_pk_add_f32 v[12:13], v[10:11], v[6:7] neg_lo:[0,1] neg_hi:[0,1]
	v_pk_add_f32 v[6:7], v[10:11], v[6:7]
	v_mov_b32_e32 v5, v2
	v_pk_add_f32 v[10:11], v[6:7], v[2:3] op_sel:[1,0] op_sel_hi:[0,1] neg_lo:[0,1] neg_hi:[0,1]
	v_pk_add_f32 v[14:15], v[8:9], v[10:11] op_sel_hi:[1,0] neg_lo:[0,1] neg_hi:[0,1]
	v_mov_b32_e32 v8, v9
	v_mov_b32_e32 v9, v7
	v_pk_mov_b32 v[10:11], v[2:3], v[10:11] op_sel:[1,0]
	v_mov_b32_e32 v14, v12
	v_pk_add_f32 v[8:9], v[8:9], v[10:11] neg_lo:[0,1] neg_hi:[0,1]
	v_mov_b32_e32 v13, v7
	v_pk_add_f32 v[2:3], v[4:5], v[8:9] neg_lo:[0,1] neg_hi:[0,1]
	s_mov_b32 s8, 0x7f800000
	v_pk_add_f32 v[4:5], v[14:15], v[2:3]
	s_load_dwordx2 s[38:39], s[36:37], 0xb8
	v_pk_add_f32 v[8:9], v[4:5], v[4:5] op_sel:[0,1] op_sel_hi:[1,0]
	v_mov_b32_e32 v39, 0x7f800000
	v_pk_add_f32 v[6:7], v[6:7], v[8:9] op_sel:[1,0] op_sel_hi:[0,1]
	v_mov_b32_e32 v5, v6
	v_pk_add_f32 v[10:11], v[4:5], v[12:13] neg_lo:[0,1] neg_hi:[0,1]
	v_mov_b32_e32 v3, v8
	v_sub_f32_e32 v4, v4, v10
	v_pk_add_f32 v[2:3], v[2:3], v[10:11] neg_lo:[0,1] neg_hi:[0,1]
	v_sub_f32_e32 v4, v12, v4
	v_add_f32_e32 v2, v2, v4
	v_add_f32_e32 v2, v2, v3
	v_add_f32_e32 v3, v6, v2
	v_sub_f32_e32 v4, v3, v6
	v_sub_f32_e32 v2, v2, v4
	v_mul_f32_e32 v4, v16, v3
	v_fma_f32 v3, v16, v3, -v4
	v_fmac_f32_e32 v3, v16, v2
	v_add_f32_e32 v2, v4, v3
	v_cmp_class_f32_e64 s[4:5], v4, s7
	v_sub_f32_e32 v5, v2, v4
	v_sub_f32_e32 v3, v3, v5
	v_cndmask_b32_e64 v2, v2, v4, s[4:5]
	v_mov_b32_e32 v4, 0x37000000
	v_cmp_eq_f32_e64 s[4:5], s9, v2
	s_waitcnt lgkmcnt(0)
; __device__ __forceinline__ void prologue(const kptr_t kp, LAS float* scr, int gw, int NGW, int lane) {
;     ...
;         if (r < 2 * IT_LAYER) {
;             const int l = r / IT_LAYER; r -= l * IT_LAYER;
;             unsigned char* wl = ws + WS_W + (size_t)l * W_LAYER;
;             if (r < IT_UP) { const int kb = r / 176, nb = r % 176; transpose_item(KPTR(const float, 7) + (size_t)l * D * 2 * DFF, 2 * DFF, (bf16_t*)(wl + W_UP1), D, up_row(32 * nb), 0, scr, 64 * kb, 32 * nb, lane); continue; } r -= IT_UP;
;             if (r < IT_DN) { const int kb = r / 32, nb = r % 32; transpose_item(KPTR(const float, 8) + (size_t)l * DFF * D, D, (bf16_t*)(wl + W_DN1), DFF, 32 * nb, 0, scr, 64 * kb, 32 * nb, lane); continue; } r -= IT_DN;
;             if (r < IT_IN) { const int kb = r / 144, nb = r % 144; transpose_item(KPTR(const float, 9) + (size_t)l * D * INC, INC, (bf16_t*)(wl + W_IN), D, 32 * nb, 0, scr, 64 * kb, 32 * nb, lane); continue; } r -= IT_IN;
;             if (r < IT_P) { const int kb = r / 32, nb = r % 32, n0 = 32 * nb; transpose_item(KPTR(const float, 16) + (size_t)l * 512 * D, D, (bf16_t*)(wl + W_PAB), D, 256 * (n0 / 128) + (n0 % 128), 0, scr, 64 * kb, n0, lane); continue; } r -= IT_P;
;             if (r < IT_P) { const int kb = r / 32, nb = r % 32, n0 = 32 * nb; transpose_item(KPTR(const float, 17) + (size_t)l * 512 * D, D, (bf16_t*)(wl + W_PAB), D, 256 * (n0 / 128) + 128 + (n0 % 128), 512, scr, 64 * kb, n0, lane); continue; } r -= IT_P;
;             if (r < IT_O) { const int kb = r / 32, nb = r % 32; transpose_item(KPTR(const float, 18) + (size_t)l * D * D, D, (bf16_t*)(wl + W_O), D, 32 * nb, 0, scr, 64 * kb, 32 * nb, lane); continue; } r -= IT_O;
;             if (r < IT_UP) { const int kb = r / 176, nb = r % 176; transpose_item(KPTR(const float, 19) + (size_t)l * D * 2 * DFF, 2 * DFF, (bf16_t*)(wl + W_UP2), D, up_row(32 * nb), 0, scr, 64 * kb, 32 * nb, lane); continue; } r -= IT_UP;
;             if (r < IT_DN) { const int kb = r / 32, nb = r % 32; transpose_item(KPTR(const float, 20) + (size_t)l * DFF * D, D, (bf16_t*)(wl + W_DN2), DFF, 32 * nb, 0, scr, 64 * kb, 32 * nb, lane); continue; } r -= IT_DN;
;             if (r < IT_Z) {
;                 const int zk0 = ((r & 255) < 128) ? 512 : 0;
;                 *(u32x4*)((bf16_t*)(wl + W_PAB) + (size_t)r * D + zk0 + 8 * lane) = (u32x4){0u, 0u, 0u, 0u}; continue; } r -= IT_Z;
;             {
	s_add_u32 s42, s38, 0xb8000
	v_and_b32_e32 v33, 63, v1
	v_cndmask_b32_e64 v4, 0, v4, s[4:5]
	v_sub_f32_e32 v5, v2, v4
	s_mov_b32 s4, 0x3fb8aa3b
	v_mul_f32_e32 v6, 0x3fb8aa3b, v5
	v_fma_f32 v7, v5, s4, -v6
	v_rndne_f32_e32 v8, v6
	v_fmamk_f32 v7, v5, 0x32a5705f, v7
	v_sub_f32_e32 v6, v6, v8
	v_add_f32_e32 v6, v6, v7
	v_exp_f32_e32 v6, v6
	v_cvt_i32_f32_e32 v7, v8
	v_cmp_neq_f32_e64 s[4:5], |v2|, s8
	s_addc_u32 s43, s39, 0
	s_add_u32 s44, s38, 0x6300000
	v_cndmask_b32_e64 v2, 0, v3, s[4:5]
	s_mov_b32 s4, 0xc2ce8ed0
	v_ldexp_f32 v3, v6, v7
	v_cmp_ngt_f32_e64 s[4:5], s4, v5
	v_add_f32_e32 v2, v4, v2
	s_addc_u32 s45, s39, 0
	v_cndmask_b32_e64 v3, 0, v3, s[4:5]
	v_cmp_nlt_f32_e64 s[4:5], s9, v5
	v_bfe_u32 v59, v1, 3, 3
	s_add_u32 s29, s38, 0x100000
	v_cndmask_b32_e64 v3, v39, v3, s[4:5]
	v_fma_f32 v2, v3, v2, v3
	v_cmp_class_f32_e64 s[4:5], v3, s7
	v_mov_b32_e32 v31, 0
	v_bfe_u32 v32, v1, 5, 1
	v_cndmask_b32_e64 v2, v2, v3, s[4:5]
	v_cmp_neq_f32_e64 s[4:5], v16, |v16|
	v_and_b32_e32 v34, 31, v1
	v_or_b32_e32 v35, 0xffe3a000, v33
	v_cndmask_b32_e64 v3, v39, 0, s[4:5]
	v_cndmask_b32_e64 v3, v3, 1.0, vcc
	v_cmp_class_f32_e64 s[4:5], v16, s7
	v_or_b32_e32 v37, 0xfff28000, v33
	s_mov_b32 s41, 0
	v_cndmask_b32_e64 v58, |v2|, v3, s[4:5]
	v_lshlrev_b32_e32 v2, 3, v33
	v_and_b32_e32 v38, 56, v2
	v_mul_u32_u24_e32 v1, 0x84, v38
	v_lshlrev_b32_e32 v3, 2, v59
	s_addc_u32 s66, s39, 0
	v_lshl_add_u32 v36, v34, 2, s6
	s_movk_i32 s67, 0x84
	v_add3_u32 v60, s6, v1, v3
	v_or_b32_e32 v61, 8, v59
	v_or_b32_e32 v62, 16, v59
	v_or_b32_e32 v63, 24, v59
	v_lshlrev_b32_e32 v64, 2, v33
	v_mov_b32_e32 v1, v32
	s_brev_b32 s68, 18
	s_mov_b32 s69, 0xfe5163ab
	s_mov_b32 s70, 0x3c439041
	s_mov_b32 s71, 0xdb629599
	s_mov_b32 s72, 0xf534ddc0
	s_mov_b32 s73, 0xfc2757d1
	s_mov_b32 s74, 0x4e441529
	s_mov_b32 s75, 0xa2f9836e
	s_mov_b32 s76, 0x3fc90fda
	s_mov_b32 s77, 0x3f22f983
	s_mov_b32 s78, 0xbfc90fda
	v_mov_b32_e32 v65, 0x3c0881c4
	v_mov_b32_e32 v66, 0xbab64f3b
	s_brev_b32 s79, 1
	s_movk_i32 s80, 0x1f8
	v_lshlrev_b32_e32 v40, 1, v2
	s_mov_b64 s[46:47], 0x2a80000
	s_movk_i32 s81, 0x5800
	s_mov_b64 s[48:49], 0x1f80000
	s_mov_b64 s[50:51], 0x1d80000
	s_mov_b64 s[52:53], 0x1980400
	s_mov_b64 s[54:55], 0x1980000
	s_movk_i32 s83, 0x4800
	s_mov_b64 s[56:57], 0x1080000
	s_mov_b64 s[58:59], 0xb00000
	s_mov_b32 s84, 0x9000
	s_mov_b64 s[60:61], 0x12000
	v_mov_b32_e32 v67, 0x1000
	s_mov_b32 s85, 0xbfb8aa3b
	s_mov_b32 s86, 0x42ce8ed0
	s_mov_b32 s87, 0xc2b17218
	s_mov_b32 s88, 0xfffee000
	s_mov_b32 s89, 0xffff7000
	s_mov_b64 s[62:63], 0x24000
	v_not_b32_e32 v68, 63
	v_not_b32_e32 v69, 31
	v_mov_b32_e32 v70, 0x7fc00000
	v_mov_b32_e32 v72, v31
	v_mov_b32_e32 v73, v31
	v_mov_b32_e32 v74, v31
	v_mov_b32_e32 v75, v31
	s_branch .LBB0_9

; __device__ __forceinline__ void prologue(const kptr_t kp, LAS float* scr, int gw, int NGW, int lane) {
;     ...
;     for (int it = gw; it < IT_TOTAL; it += NGW) {
.LBB0_8:
	s_add_i32 s3, s3, s99
	s_cmp_lt_i32 s3, s100
	s_cbranch_scc0 .Lcv_ret

; #define LAS __attribute__((address_space(3)))
; #define PH_BEGIN() const kptr_t kp = kargs(); unsigned char* const ws = KWS(); (void)ws; int tid_ = threadIdx.x; asm volatile("" : "+v"(tid_)); const int lane = tid_ & 63, wave = __builtin_amdgcn_readfirstlane(tid_ >> 6); \
;     const int gw = blockIdx.x * NWAVES + wave, NGW = gridDim.x * NWAVES; (void)lane; (void)gw; (void)NGW
; __device__ __forceinline__ void prologue(const kptr_t kp, LAS float* scr, int gw, int NGW, int lane) {
;     ...
;     for (int it = gw; it < IT_TOTAL; it += NGW) {
; __global__ void __launch_bounds__(NTHREADS, 2) mega_fwd(Args a) {
;     ...
;     { PH_BEGIN(); prologue(kp, (LAS float*)(lds + wave * 16384), gw, NGW, lane); }
.Lcv_ret:
	s_cmp_lg_u32 s101, 0
	s_cbranch_scc1 .Lcv_r1
	s_movk_i32 s98, 0x7180
	s_movk_i32 s100, 0x79d0
	s_mov_b32 s101, 1
	s_branch .Lcv_entry
.Lcv_r1:
	s_cmp_eq_u32 s101, 11
	s_cbranch_scc1 .Lslot_1_ret
	s_cmp_eq_u32 s101, 12
	s_cbranch_scc1 .Lslot_2_ret
	s_cmp_gt_u32 s101, 12
	s_cbranch_scc1 .Lrt_hop2

; #define PH_BEGIN() const kptr_t kp = kargs(); unsigned char* const ws = KWS(); (void)ws; int tid_ = threadIdx.x; asm volatile("" : "+v"(tid_)); const int lane = tid_ & 63, wave = __builtin_amdgcn_readfirstlane(tid_ >> 6); \
;     const int gw = blockIdx.x * NWAVES + wave, NGW = gridDim.x * NWAVES; (void)lane; (void)gw; (void)NGW
; #define GSYNC(j) do { gbar(2 * (L * 11 + (j))); gbar(2 * (L * 11 + (j)) + 1); } while (0)
; #define GSYNC(j) xbar(lds)
; __device__ __forceinline__ void prologue(const kptr_t kp, LAS float* scr, int gw, int NGW, int lane) {
;     ...
;             if (r < IT_DN) { const int kb = r / 32, nb = r % 32; transpose_item(KPTR(const float, 8) + (size_t)l * DFF * D, D, (bf16_t*)(wl + W_DN1), DFF, 32 * nb, 0, scr, 64 * kb, 32 * nb, lane); continue; } r -= IT_DN;
;             if (r < IT_IN) { const int kb = r / 144, nb = r % 144; transpose_item(KPTR(const float, 9) + (size_t)l * D * INC, INC, (bf16_t*)(wl + W_IN), D, 32 * nb, 0, scr, 64 * kb, 32 * nb, lane); continue; } r -= IT_IN;
;             if (r < IT_P) { const int kb = r / 32, nb = r % 32, n0 = 32 * nb; transpose_item(KPTR(const float, 16) + (size_t)l * 512 * D, D, (bf16_t*)(wl + W_PAB), D, 256 * (n0 / 128) + (n0 % 128), 0, scr, 64 * kb, n0, lane); continue; } r -= IT_P;
;             if (r < IT_P) { const int kb = r / 32, nb = r % 32, n0 = 32 * nb; transpose_item(KPTR(const float, 17) + (size_t)l * 512 * D, D, (bf16_t*)(wl + W_PAB), D, 256 * (n0 / 128) + 128 + (n0 % 128), 512, scr, 64 * kb, n0, lane); continue; } r -= IT_P;
;             if (r < IT_O) { const int kb = r / 32, nb = r % 32; transpose_item(KPTR(const float, 18) + (size_t)l * D * D, D, (bf16_t*)(wl + W_O), D, 32 * nb, 0, scr, 64 * kb, 32 * nb, lane); continue; } r -= IT_O;
; template <int L> __device__ __forceinline__ void layer_fwd(cg::grid_group& grid, LAS unsigned char* lds) {
;     ...
;     { PH_BEGIN(); run_gemm(lds, (const bf16_t*)(ws + WS_H), (const bf16_t*)(ws + WL + W_UP1), MALL, 2 * DFF, D, pg8::EpiSwiGLU{(bf16_t*)(ws + WS_G)}); }
;     GSYNC(1);
.LBB0_239:
	s_cmp_lt_u32 s2, 44
	s_cbranch_scc1 .Lslot_1_skip
	v_writelane_b32 v250, s3, 0
	v_writelane_b32 v250, s4, 1
	v_writelane_b32 v250, s5, 2
	v_writelane_b32 v250, s6, 3
	v_writelane_b32 v250, s7, 4
	v_writelane_b32 v250, s8, 5
	v_writelane_b32 v250, s9, 6
	v_writelane_b32 v250, s10, 7
	v_writelane_b32 v250, s11, 8
	v_writelane_b32 v250, s12, 9
	v_writelane_b32 v250, s13, 10
	v_writelane_b32 v250, s14, 11
	v_writelane_b32 v250, s15, 12
	v_writelane_b32 v250, s16, 13
	v_writelane_b32 v250, s17, 14
	v_writelane_b32 v250, s18, 15
	v_writelane_b32 v250, s19, 16
	v_writelane_b32 v250, s20, 17
	v_writelane_b32 v250, s21, 18
	v_writelane_b32 v250, s22, 19
	v_writelane_b32 v250, s23, 20
	v_writelane_b32 v250, s24, 21
	v_writelane_b32 v250, s25, 22
	v_writelane_b32 v250, s26, 23
	v_writelane_b32 v250, s27, 24
	v_writelane_b32 v250, s28, 25
	v_writelane_b32 v250, s29, 26
	v_writelane_b32 v250, s30, 27
	v_writelane_b32 v250, s31, 28
	v_writelane_b32 v250, s32, 29
	v_writelane_b32 v250, s33, 30
	v_writelane_b32 v250, s34, 31
	v_writelane_b32 v250, s35, 32
	v_writelane_b32 v250, s36, 33
	v_writelane_b32 v250, s37, 34
	v_writelane_b32 v250, s38, 35
	v_writelane_b32 v250, s39, 36
	v_writelane_b32 v250, s40, 37
	v_writelane_b32 v250, s41, 38
	v_writelane_b32 v250, s42, 39
	v_writelane_b32 v250, s43, 40
	v_writelane_b32 v250, s44, 41
	v_writelane_b32 v250, s45, 42
	v_writelane_b32 v250, s46, 43
	v_writelane_b32 v250, s47, 44
	v_writelane_b32 v250, s48, 45
	v_writelane_b32 v250, s49, 46
	v_writelane_b32 v250, s50, 47
	v_writelane_b32 v250, s51, 48
	v_writelane_b32 v250, s52, 49
	v_writelane_b32 v250, s53, 50
	v_writelane_b32 v250, s54, 51
	v_writelane_b32 v250, s55, 52
	v_writelane_b32 v250, s56, 53
	v_writelane_b32 v250, s57, 54
	v_writelane_b32 v250, s58, 55
	v_writelane_b32 v250, s59, 56
	v_writelane_b32 v250, s60, 57
	v_writelane_b32 v250, s61, 58
	v_writelane_b32 v250, s62, 59
	v_writelane_b32 v250, s63, 60
	v_writelane_b32 v250, s64, 61
	v_writelane_b32 v250, s65, 62
	v_writelane_b32 v250, s66, 63
	v_writelane_b32 v251, s67, 0
	v_writelane_b32 v251, s68, 1
	v_writelane_b32 v251, s69, 2
	v_writelane_b32 v251, s70, 3
	v_writelane_b32 v251, s71, 4
	v_writelane_b32 v251, s72, 5
	v_writelane_b32 v251, s73, 6
	v_writelane_b32 v251, s74, 7
	v_writelane_b32 v251, s75, 8
	v_writelane_b32 v251, s76, 9
	v_writelane_b32 v251, s77, 10
	v_writelane_b32 v251, s78, 11
	v_writelane_b32 v251, s79, 12
	v_writelane_b32 v251, s80, 13
	v_writelane_b32 v251, s81, 14
	v_writelane_b32 v251, s82, 15
	v_writelane_b32 v251, s83, 16
	v_writelane_b32 v251, s84, 17
	v_writelane_b32 v251, s85, 18
	v_writelane_b32 v251, s86, 19
	v_writelane_b32 v251, s87, 20
	v_writelane_b32 v251, s88, 21
	v_writelane_b32 v251, s89, 22
	v_writelane_b32 v251, s90, 23
	v_writelane_b32 v251, s91, 24
	v_writelane_b32 v251, s92, 25
	v_writelane_b32 v251, s93, 26
	v_writelane_b32 v251, s94, 27
	v_writelane_b32 v251, s95, 28
	v_writelane_b32 v251, s96, 29
	v_writelane_b32 v251, s97, 30
	v_mov_b32_e32 v236, v200
	v_mov_b32_e32 v237, v201
	v_mov_b32_e32 v238, v202
	v_mov_b32_e32 v239, v203
	v_mov_b32_e32 v240, v204
	v_mov_b32_e32 v241, v205
	v_mov_b32_e32 v242, v206
	v_mov_b32_e32 v243, v207
	v_mov_b32_e32 v244, v208
	v_mov_b32_e32 v245, v209
	v_mov_b32_e32 v246, v210
	v_mov_b32_e32 v247, v211
	s_mov_b32 s98, 0xe20
	s_mov_b32 s99, 0x6a0
	s_mov_b32 s100, 0x2200
	s_mov_b32 s101, 11
	s_branch .Lcv_entry
.Lslot_1_ret:
	v_mov_b32_e32 v200, v236
	v_mov_b32_e32 v201, v237
	v_mov_b32_e32 v202, v238
	v_mov_b32_e32 v203, v239
	v_mov_b32_e32 v204, v240
	v_mov_b32_e32 v205, v241
	v_mov_b32_e32 v206, v242
	v_mov_b32_e32 v207, v243
	v_mov_b32_e32 v208, v244
	v_mov_b32_e32 v209, v245
	v_mov_b32_e32 v210, v246
	v_mov_b32_e32 v211, v247
	v_readlane_b32 s3, v250, 0
	v_readlane_b32 s4, v250, 1
	v_readlane_b32 s5, v250, 2
	v_readlane_b32 s6, v250, 3
	v_readlane_b32 s7, v250, 4
	v_readlane_b32 s8, v250, 5
	v_readlane_b32 s9, v250, 6
	v_readlane_b32 s10, v250, 7
	v_readlane_b32 s11, v250, 8
	v_readlane_b32 s12, v250, 9
	v_readlane_b32 s13, v250, 10
	v_readlane_b32 s14, v250, 11
	v_readlane_b32 s15, v250, 12
	v_readlane_b32 s16, v250, 13
	v_readlane_b32 s17, v250, 14
	v_readlane_b32 s18, v250, 15
	v_readlane_b32 s19, v250, 16
	v_readlane_b32 s20, v250, 17
	v_readlane_b32 s21, v250, 18
	v_readlane_b32 s22, v250, 19
	v_readlane_b32 s23, v250, 20
	v_readlane_b32 s24, v250, 21
	v_readlane_b32 s25, v250, 22
	v_readlane_b32 s26, v250, 23
	v_readlane_b32 s27, v250, 24
	v_readlane_b32 s28, v250, 25
	v_readlane_b32 s29, v250, 26
	v_readlane_b32 s30, v250, 27
	v_readlane_b32 s31, v250, 28
	v_readlane_b32 s32, v250, 29
	v_readlane_b32 s33, v250, 30
	v_readlane_b32 s34, v250, 31
	v_readlane_b32 s35, v250, 32
	v_readlane_b32 s36, v250, 33
	v_readlane_b32 s37, v250, 34
	v_readlane_b32 s38, v250, 35
	v_readlane_b32 s39, v250, 36
	v_readlane_b32 s40, v250, 37
	v_readlane_b32 s41, v250, 38
	v_readlane_b32 s42, v250, 39
	v_readlane_b32 s43, v250, 40
	v_readlane_b32 s44, v250, 41
	v_readlane_b32 s45, v250, 42
	v_readlane_b32 s46, v250, 43
	v_readlane_b32 s47, v250, 44
	v_readlane_b32 s48, v250, 45
	v_readlane_b32 s49, v250, 46
	v_readlane_b32 s50, v250, 47
	v_readlane_b32 s51, v250, 48
	v_readlane_b32 s52, v250, 49
	v_readlane_b32 s53, v250, 50
	v_readlane_b32 s54, v250, 51
	v_readlane_b32 s55, v250, 52
	v_readlane_b32 s56, v250, 53
	v_readlane_b32 s57, v250, 54
	v_readlane_b32 s58, v250, 55
	v_readlane_b32 s59, v250, 56
	v_readlane_b32 s60, v250, 57
	v_readlane_b32 s61, v250, 58
	v_readlane_b32 s62, v250, 59
	v_readlane_b32 s63, v250, 60
	v_readlane_b32 s64, v250, 61
	v_readlane_b32 s65, v250, 62
	v_readlane_b32 s66, v250, 63
	v_readlane_b32 s67, v251, 0
	v_readlane_b32 s68, v251, 1
	v_readlane_b32 s69, v251, 2
	v_readlane_b32 s70, v251, 3
	v_readlane_b32 s71, v251, 4
	v_readlane_b32 s72, v251, 5
	v_readlane_b32 s73, v251, 6
	v_readlane_b32 s74, v251, 7
	v_readlane_b32 s75, v251, 8
	v_readlane_b32 s76, v251, 9
	v_readlane_b32 s77, v251, 10
	v_readlane_b32 s78, v251, 11
	v_readlane_b32 s79, v251, 12
	v_readlane_b32 s80, v251, 13
	v_readlane_b32 s81, v251, 14
	v_readlane_b32 s82, v251, 15
	v_readlane_b32 s83, v251, 16
	v_readlane_b32 s84, v251, 17
	v_readlane_b32 s85, v251, 18
	v_readlane_b32 s86, v251, 19
	v_readlane_b32 s87, v251, 20
	v_readlane_b32 s88, v251, 21
	v_readlane_b32 s89, v251, 22
	v_readlane_b32 s90, v251, 23
	v_readlane_b32 s91, v251, 24
	v_readlane_b32 s92, v251, 25
	v_readlane_b32 s93, v251, 26
	v_readlane_b32 s94, v251, 27
	v_readlane_b32 s95, v251, 28
	v_readlane_b32 s96, v251, 29
	v_readlane_b32 s97, v251, 30
	s_nop 3

; __device__ __forceinline__ unsigned cvtpk_s(float lo, float hi) { f32x2_t v = {lo, hi}; bf16x2_t b = __builtin_convertvector(v, bf16x2_t); return __builtin_bit_cast(unsigned, b); }
; #define KIN(i) KPTR(const float, i)
; #define PH_BEGIN() const kptr_t kp = kargs(); unsigned char* const ws = KWS(); (void)ws; int tid_ = threadIdx.x; asm volatile("" : "+v"(tid_)); const int lane = tid_ & 63, wave = __builtin_amdgcn_readfirstlane(tid_ >> 6); \
;     const int gw = blockIdx.x * NWAVES + wave, NGW = gridDim.x * NWAVES; (void)lane; (void)gw; (void)NGW
; #define GSYNC(j) xbar(lds)
; __device__ __forceinline__ void prologue(const kptr_t kp, LAS float* scr, int gw, int NGW, int lane) {
;     ...
;             if (r < IT_UP) { const int kb = r / 176, nb = r % 176; transpose_item(KPTR(const float, 19) + (size_t)l * D * 2 * DFF, 2 * DFF, (bf16_t*)(wl + W_UP2), D, up_row(32 * nb), 0, scr, 64 * kb, 32 * nb, lane); continue; } r -= IT_UP;
;             if (r < IT_DN) { const int kb = r / 32, nb = r % 32; transpose_item(KPTR(const float, 20) + (size_t)l * DFF * D, D, (bf16_t*)(wl + W_DN2), DFF, 32 * nb, 0, scr, 64 * kb, 32 * nb, lane); continue; } r -= IT_DN;
;             if (r < IT_Z) {
;                 const int zk0 = ((r & 255) < 128) ? 512 : 0;
;                 *(u32x4*)((bf16_t*)(wl + W_PAB) + (size_t)r * D + zk0 + 8 * lane) = (u32x4){0u, 0u, 0u, 0u}; continue; } r -= IT_Z;
;             {
;                 const float* s = KPTR(const float, 14) + (size_t)l * 65536 + (size_t)(r * 64 + lane) * 8; const f32x4 v0 = *(const f32x4*)s, v1 = *(const f32x4*)(s + 4);
;                 u32x4 o; o.x = cvtpk_s(v0[0], v0[1]); o.y = cvtpk_s(v0[2], v0[3]); o.z = cvtpk_s(v1[0], v1[1]); o.w = cvtpk_s(v1[2], v1[3]);
;                 *(u32x4*)((bf16_t*)(wl + W_S) + (size_t)(r * 64 + lane) * 8) = o; continue; }
; template <int L> __device__ __forceinline__ void layer_fwd(cg::grid_group& grid, LAS unsigned char* lds) {
;     ...
;     { PH_BEGIN(); run_gemm(lds, (const bf16_t*)(ws + WS_H), (const bf16_t*)(ws + WL + W_IN), MALL, INC, D,
;                            pg8::EpiWin{(bf16_t*)(ws + WS_QU), (bf16_t*)(ws + WS_KB), (bf16_t*)(ws + WS_VT), (bf16_t*)(ws + WS_VST), (bf16_t*)(ws + WS_GT), KIN(10) + (size_t)L * 2048,
;                                        (const f32x4*)(ws + CTL_ROPE), (const f32x4*)(ws + CTL_ROPE) + 256 * 8, (float*)(ws + STL), QSCALE, lds + 131072}); }
;     GSYNC(4);
.LBB0_847:
	s_cmp_lt_u32 s2, 36
	s_cbranch_scc1 .Lslot_2_skip
	v_writelane_b32 v250, s3, 0
	v_writelane_b32 v250, s4, 1
	v_writelane_b32 v250, s5, 2
	v_writelane_b32 v250, s6, 3
	v_writelane_b32 v250, s7, 4
	v_writelane_b32 v250, s8, 5
	v_writelane_b32 v250, s9, 6
	v_writelane_b32 v250, s10, 7
	v_writelane_b32 v250, s11, 8
	v_writelane_b32 v250, s12, 9
	v_writelane_b32 v250, s13, 10
	v_writelane_b32 v250, s14, 11
	v_writelane_b32 v250, s15, 12
	v_writelane_b32 v250, s16, 13
	v_writelane_b32 v250, s17, 14
	v_writelane_b32 v250, s18, 15
	v_writelane_b32 v250, s19, 16
	v_writelane_b32 v250, s20, 17
	v_writelane_b32 v250, s21, 18
	v_writelane_b32 v250, s22, 19
	v_writelane_b32 v250, s23, 20
	v_writelane_b32 v250, s24, 21
	v_writelane_b32 v250, s25, 22
	v_writelane_b32 v250, s26, 23
	v_writelane_b32 v250, s27, 24
	v_writelane_b32 v250, s28, 25
	v_writelane_b32 v250, s29, 26
	v_writelane_b32 v250, s30, 27
	v_writelane_b32 v250, s31, 28
	v_writelane_b32 v250, s32, 29
	v_writelane_b32 v250, s33, 30
	v_writelane_b32 v250, s34, 31
	v_writelane_b32 v250, s35, 32
	v_writelane_b32 v250, s36, 33
	v_writelane_b32 v250, s37, 34
	v_writelane_b32 v250, s38, 35
	v_writelane_b32 v250, s39, 36
	v_writelane_b32 v250, s40, 37
	v_writelane_b32 v250, s41, 38
	v_writelane_b32 v250, s42, 39
	v_writelane_b32 v250, s43, 40
	v_writelane_b32 v250, s44, 41
	v_writelane_b32 v250, s45, 42
	v_writelane_b32 v250, s46, 43
	v_writelane_b32 v250, s47, 44
	v_writelane_b32 v250, s48, 45
	v_writelane_b32 v250, s49, 46
	v_writelane_b32 v250, s50, 47
	v_writelane_b32 v250, s51, 48
	v_writelane_b32 v250, s52, 49
	v_writelane_b32 v250, s53, 50
	v_writelane_b32 v250, s54, 51
	v_writelane_b32 v250, s55, 52
	v_writelane_b32 v250, s56, 53
	v_writelane_b32 v250, s57, 54
	v_writelane_b32 v250, s58, 55
	v_writelane_b32 v250, s59, 56
	v_writelane_b32 v250, s60, 57
	v_writelane_b32 v250, s61, 58
	v_writelane_b32 v250, s62, 59
	v_writelane_b32 v250, s63, 60
	v_writelane_b32 v250, s64, 61
	v_writelane_b32 v250, s65, 62
	v_writelane_b32 v250, s66, 63
	v_writelane_b32 v251, s67, 0
	v_writelane_b32 v251, s68, 1
	v_writelane_b32 v251, s69, 2
	v_writelane_b32 v251, s70, 3
	v_writelane_b32 v251, s71, 4
	v_writelane_b32 v251, s72, 5
	v_writelane_b32 v251, s73, 6
	v_writelane_b32 v251, s74, 7
	v_writelane_b32 v251, s75, 8
	v_writelane_b32 v251, s76, 9
	v_writelane_b32 v251, s77, 10
	v_writelane_b32 v251, s78, 11
	v_writelane_b32 v251, s79, 12
	v_writelane_b32 v251, s80, 13
	v_writelane_b32 v251, s81, 14
	v_writelane_b32 v251, s82, 15
	v_writelane_b32 v251, s83, 16
	v_writelane_b32 v251, s84, 17
	v_writelane_b32 v251, s85, 18
	v_writelane_b32 v251, s86, 19
	v_writelane_b32 v251, s87, 20
	v_writelane_b32 v251, s88, 21
	v_writelane_b32 v251, s89, 22
	v_writelane_b32 v251, s90, 23
	v_writelane_b32 v251, s91, 24
	v_writelane_b32 v251, s92, 25
	v_writelane_b32 v251, s93, 26
	v_writelane_b32 v251, s94, 27
	v_writelane_b32 v251, s95, 28
	v_writelane_b32 v251, s96, 29
	v_writelane_b32 v251, s97, 30
	v_mov_b32_e32 v236, v200
	v_mov_b32_e32 v237, v201
	v_mov_b32_e32 v238, v202
	v_mov_b32_e32 v239, v203
	v_mov_b32_e32 v240, v204
	v_mov_b32_e32 v241, v205
	v_mov_b32_e32 v242, v206
	v_mov_b32_e32 v243, v207
	v_mov_b32_e32 v244, v208
	v_mov_b32_e32 v245, v209
	v_mov_b32_e32 v246, v210
	v_mov_b32_e32 v247, v211
	s_mov_b32 s98, 0x20e0
	s_mov_b32 s99, 0x6e0
	s_mov_b32 s100, 0x3b00
	s_mov_b32 s101, 12
	s_branch .Lcv_entry

; __device__ __forceinline__ void prologue(const kptr_t kp, LAS float* scr, int gw, int NGW, int lane) {
;     ...
;     for (int it = gw; it < IT_TOTAL; it += NGW) {
.Lcv_hop2:
	s_branch .Lcv_entry
.Lrt_hop2:
	s_cmp_eq_u32 s101, 13
	s_cbranch_scc1 .Lslot_3_ret
	s_cmp_eq_u32 s101, 14
	s_cbranch_scc1 .Lslot_4_ret
	s_branch .Lrt_hop3

; #define LAS __attribute__((address_space(3)))
; template <int L> __device__ __forceinline__ void layer_fwd(cg::grid_group& grid, LAS unsigned char* lds) {
;     ...
;         const LAS float* rpbl = (const LAS float*)(lds + LDS_RPB); LAS unsigned char* otl = lds + LDS_OT + wave * 2048;
;         const int lw = (blockIdx.x >> 3) * 8 + wave, xcd = blockIdx.x & 7, hp = (blockIdx.x >> 3) & 3;
; #pragma unroll 1
;         for (int s = 0; s < 10; ++s) {
;             const int bb = s / 5, k = s - 5 * bb;
;             int u, hs;
;             if (k == 0) {
;                 __syncthreads();
;                 const int h0 = hp * 2; int tid = threadIdx.x; asm volatile("" : "+v"(tid));
; #pragma unroll
;                 for (int i = 0; i < 8; ++i) { const int ca = tid + 512 * i, hq = ca >> 11, ci = ca & 2047, key = ci >> 3, c = ci & 7;
;                     const u32x4 v = *(const u32x4*)(KBp + ((size_t)(h0 + hq) * MALL + (MX + bb * 256 + key)) * 64 + c * 8);
;                     *(LAS u32x4*)(lds + LDS_CK + hq * 32768 + key * 128 + ((c ^ ((((key >> 3) & 3) * 2) + ((key >> 1) & 1))) << 4)) = v; }
; #pragma unroll
;                 for (int i = 0; i < 8; ++i) { const int ca = tid + 512 * i, hq = ca >> 11, ci = ca & 2047, blk = ci >> 6, d = ci & 63;
;                     const u32x4 v = *(const u32x4*)(VTp + ((size_t)(((MX + bb * 256) >> 3) + blk) * 512 + (h0 + hq) * 64 + d) * 8);
;                     *(LAS u32x4*)(lds + LDS_CV + hq * 32768 + d * 512 + ((blk ^ (d & 15)) << 4)) = v; }
;                 __syncthreads();
;             }
;             if (k < 4) { const int pair = (bb * 4 + k) * 8 + (lw >> 5), rr = 32 * xcd + (pair & 31); u = (bb << 13) | (rr << 5) | (lw & 31); hs = wave >> 2; }
;             else {
;                 if (L != 0 || xcd >= 4 || wave != 0) continue;
;                 const int idx = xcd * 8 + (blockIdx.x >> 5); hs = idx >> 4;
;                 u = 16384 + (bb << 7) + (((idx >> 2) & 3) << 5) + ((hp * 2 + hs) << 2) + (idx & 3);
.LBB0_902:
	s_or_b64 exec, exec, s[14:15]
	s_and_b32 s3, s2, 7
	s_and_b32 s7, s2, 3
	s_lshl_b32 s7, s7, 3
	s_lshr_b32 s8, s2, 5
	s_add_i32 s7, s7, s8
	s_bfe_u32 s6, s2, 0x20003
	s_lshr_b32 s39, s7, 4
	s_lshl_b32 s8, s7, 3
	s_lshl_b32 s9, s39, 2
	s_lshl_b32 s40, s6, 1
	s_lshl_b32 s10, s6, 3
	s_bfe_u32 s16, s2, 0x20005
	s_and_b32 s18, s2, -8
	v_readfirstlane_b32 s17, v2
	s_cmp_lt_u32 s3, 4
	s_cselect_b64 s[6:7], -1, 0
	s_and_b32 s8, s8, 0x60
	s_lshl_b32 s41, s3, 10
	s_ashr_i32 s3, s17, 6
	s_add_u32 s12, s4, 0xe700000
	s_addc_u32 s13, s5, 0
	s_add_u32 s14, s4, 0x10780000
	s_addc_u32 s15, s5, 0
	s_add_u32 s20, s4, 0xa600000
	s_addc_u32 s21, s5, 0
	s_add_u32 s42, s4, 0x6500000
	s_addc_u32 s43, s5, 0
	s_lshl_b32 s4, s3, 11
	s_add_i32 s44, s4, 0
	s_add_i32 s44, s44, 0x23a20
	s_add_i32 s3, s3, s18
	s_cmp_lt_u32 s17, 64
	s_cselect_b64 s[4:5], -1, 0
	s_and_b32 s45, s3, 0x3e0
	s_and_b32 s46, s3, 31
	s_add_i32 s3, s10, s9
	s_add_i32 s3, s3, s8
	s_or_b32 s49, s3, s16
	v_and_b32_e32 v201, 63, v2
	s_and_b64 s[22:23], s[6:7], s[4:5]
	s_andn2_b64 s[100:101], s[4:5], s[6:7]
	s_ashr_i32 s47, s17, 8
	s_movk_i32 s48, 0x4000
	s_addk_i32 s49, 0x4000
	s_mov_b32 s50, 0x8000
	s_mov_b32 s51, 0x8100
	s_mov_b32 s52, 0x204000
	s_mov_b32 s53, 0x10000
	s_add_i32 s3, 0, 0x10000
	s_movk_i32 s54, 0x6000
	s_mov_b32 s55, 0xa000
	s_mov_b32 s56, 0xc000
	s_mov_b32 s57, 0xe000
	s_mov_b32 s58, 0x30000
	s_mov_b32 s59, 0x40000
	s_mov_b32 s60, 0x50000
	s_mov_b32 s61, 0x60000
	s_mov_b32 s62, 0x70000
	s_movk_i32 s63, 0x7c
	s_mov_b32 s64, 0xff800000
	s_movk_i32 s65, 0x7fff
	v_mbcnt_hi_u32_b32 v213, -1, v212
	v_mov_b32_e32 v214, 0xff800000
	s_mov_b32 s66, 0
	s_waitcnt lgkmcnt(0)
	s_barrier
	v_writelane_b32 v252, s18, 8
	s_branch .LBB0_906

; template <int L> __device__ __forceinline__ void layer_fwd(cg::grid_group& grid, LAS unsigned char* lds) {
;     ...
;             if (k < 4) { const int pair = (bb * 4 + k) * 8 + (lw >> 5), rr = 32 * xcd + (pair & 31); u = (bb << 13) | (rr << 5) | (lw & 31); hs = wave >> 2; }
;             else {
;                 if (L != 0 || xcd >= 4 || wave != 0) continue;
;                 const int idx = xcd * 8 + (blockIdx.x >> 5); hs = idx >> 4;
;                 u = 16384 + (bb << 7) + (((idx >> 2) & 3) << 5) + ((hp * 2 + hs) << 2) + (idx & 3);
;             }
;             attn_unit(u, KBp, VTp, QUp, OBp, rpbl, otl, lds + LDS_CK + hs * 32768, lds + LDS_CV + hs * 32768, lane);
.LBB0_908:
	s_mov_b64 s[36:37], 0
	s_and_b64 vcc, s[4:5], exec
	s_cselect_b64 vcc, s[100:101], s[22:23]
	s_and_b64 vcc, exec, vcc
	s_mov_b64 s[26:27], 0
	s_cbranch_vccnz .LBB0_913
	s_and_b64 vcc, exec, s[36:37]
	s_mov_b32 s6, s39
	s_cbranch_vccnz .LBB0_914

; #define PH_BEGIN() const kptr_t kp = kargs(); unsigned char* const ws = KWS(); (void)ws; int tid_ = threadIdx.x; asm volatile("" : "+v"(tid_)); const int lane = tid_ & 63, wave = __builtin_amdgcn_readfirstlane(tid_ >> 6); \
;     const int gw = blockIdx.x * NWAVES + wave, NGW = gridDim.x * NWAVES; (void)lane; (void)gw; (void)NGW
; #define GSYNC(j) do { gbar(2 * (L * 11 + (j))); gbar(2 * (L * 11 + (j)) + 1); } while (0)
; #define GSYNC(j) xbar(lds)
; __device__ __forceinline__ void prologue(const kptr_t kp, LAS float* scr, int gw, int NGW, int lane) {
;     ...
;             if (r < IT_UP) { const int kb = r / 176, nb = r % 176; transpose_item(KPTR(const float, 7) + (size_t)l * D * 2 * DFF, 2 * DFF, (bf16_t*)(wl + W_UP1), D, up_row(32 * nb), 0, scr, 64 * kb, 32 * nb, lane); continue; } r -= IT_UP;
;             if (r < IT_DN) { const int kb = r / 32, nb = r % 32; transpose_item(KPTR(const float, 8) + (size_t)l * DFF * D, D, (bf16_t*)(wl + W_DN1), DFF, 32 * nb, 0, scr, 64 * kb, 32 * nb, lane); continue; } r -= IT_DN;
; template <int L> __device__ __forceinline__ void layer_fwd(cg::grid_group& grid, LAS unsigned char* lds) {
;     ...
;     { PH_BEGIN(); run_gemm<pg8::EpiMerge, 8>(lds, (const bf16_t*)(ws + WS_H), (const bf16_t*)(ws + WL + W_PAB), Mr, 2048, D, pg8::EpiMerge{(const bf16_t*)(ws + WS_GT), (bf16_t*)(ws + WS_MRG)}); }
;     GSYNC(6);
.LBB0_1054:
	s_cmp_lt_u32 s2, 16
	s_cbranch_scc1 .Lslot_3_skip
	v_writelane_b32 v250, s3, 0
	v_writelane_b32 v250, s4, 1
	v_writelane_b32 v250, s5, 2
	v_writelane_b32 v250, s6, 3
	v_writelane_b32 v250, s7, 4
	v_writelane_b32 v250, s8, 5
	v_writelane_b32 v250, s9, 6
	v_writelane_b32 v250, s10, 7
	v_writelane_b32 v250, s11, 8
	v_writelane_b32 v250, s12, 9
	v_writelane_b32 v250, s13, 10
	v_writelane_b32 v250, s14, 11
	v_writelane_b32 v250, s15, 12
	v_writelane_b32 v250, s16, 13
	v_writelane_b32 v250, s17, 14
	v_writelane_b32 v250, s18, 15
	v_writelane_b32 v250, s19, 16
	v_writelane_b32 v250, s20, 17
	v_writelane_b32 v250, s21, 18
	v_writelane_b32 v250, s22, 19
	v_writelane_b32 v250, s23, 20
	v_writelane_b32 v250, s24, 21
	v_writelane_b32 v250, s25, 22
	v_writelane_b32 v250, s26, 23
	v_writelane_b32 v250, s27, 24
	v_writelane_b32 v250, s28, 25
	v_writelane_b32 v250, s29, 26
	v_writelane_b32 v250, s30, 27
	v_writelane_b32 v250, s31, 28
	v_writelane_b32 v250, s32, 29
	v_writelane_b32 v250, s33, 30
	v_writelane_b32 v250, s34, 31
	v_writelane_b32 v250, s35, 32
	v_writelane_b32 v250, s36, 33
	v_writelane_b32 v250, s37, 34
	v_writelane_b32 v250, s38, 35
	v_writelane_b32 v250, s39, 36
	v_writelane_b32 v250, s40, 37
	v_writelane_b32 v250, s41, 38
	v_writelane_b32 v250, s42, 39
	v_writelane_b32 v250, s43, 40
	v_writelane_b32 v250, s44, 41
	v_writelane_b32 v250, s45, 42
	v_writelane_b32 v250, s46, 43
	v_writelane_b32 v250, s47, 44
	v_writelane_b32 v250, s48, 45
	v_writelane_b32 v250, s49, 46
	v_writelane_b32 v250, s50, 47
	v_writelane_b32 v250, s51, 48
	v_writelane_b32 v250, s52, 49
	v_writelane_b32 v250, s53, 50
	v_writelane_b32 v250, s54, 51
	v_writelane_b32 v250, s55, 52
	v_writelane_b32 v250, s56, 53
	v_writelane_b32 v250, s57, 54
	v_writelane_b32 v250, s58, 55
	v_writelane_b32 v250, s59, 56
	v_writelane_b32 v250, s60, 57
	v_writelane_b32 v250, s61, 58
	v_writelane_b32 v250, s62, 59
	v_writelane_b32 v250, s63, 60
	v_writelane_b32 v250, s64, 61
	v_writelane_b32 v250, s65, 62
	v_writelane_b32 v250, s66, 63
	v_writelane_b32 v251, s67, 0
	v_writelane_b32 v251, s68, 1
	v_writelane_b32 v251, s69, 2
	v_writelane_b32 v251, s70, 3
	v_writelane_b32 v251, s71, 4
	v_writelane_b32 v251, s72, 5
	v_writelane_b32 v251, s73, 6
	v_writelane_b32 v251, s74, 7
	v_writelane_b32 v251, s75, 8
	v_writelane_b32 v251, s76, 9
	v_writelane_b32 v251, s77, 10
	v_writelane_b32 v251, s78, 11
	v_writelane_b32 v251, s79, 12
	v_writelane_b32 v251, s80, 13
	v_writelane_b32 v251, s81, 14
	v_writelane_b32 v251, s82, 15
	v_writelane_b32 v251, s83, 16
	v_writelane_b32 v251, s84, 17
	v_writelane_b32 v251, s85, 18
	v_writelane_b32 v251, s86, 19
	v_writelane_b32 v251, s87, 20
	v_writelane_b32 v251, s88, 21
	v_writelane_b32 v251, s89, 22
	v_writelane_b32 v251, s90, 23
	v_writelane_b32 v251, s91, 24
	v_writelane_b32 v251, s92, 25
	v_writelane_b32 v251, s93, 26
	v_writelane_b32 v251, s94, 27
	v_writelane_b32 v251, s95, 28
	v_writelane_b32 v251, s96, 29
	v_writelane_b32 v251, s97, 30
	v_mov_b32_e32 v236, v200
	v_mov_b32_e32 v237, v201
	v_mov_b32_e32 v238, v202
	v_mov_b32_e32 v239, v203
	v_mov_b32_e32 v240, v204
	v_mov_b32_e32 v241, v205
	v_mov_b32_e32 v242, v206
	v_mov_b32_e32 v243, v207
	v_mov_b32_e32 v244, v208
	v_mov_b32_e32 v245, v209
	v_mov_b32_e32 v246, v210
	v_mov_b32_e32 v247, v211
	s_mov_b32 s98, 0x3a80
	s_mov_b32 s99, 0x780
	s_mov_b32 s100, 0x4b80
	s_mov_b32 s101, 13
	s_branch .Lcv_hop2

; #define PH_BEGIN() const kptr_t kp = kargs(); unsigned char* const ws = KWS(); (void)ws; int tid_ = threadIdx.x; asm volatile("" : "+v"(tid_)); const int lane = tid_ & 63, wave = __builtin_amdgcn_readfirstlane(tid_ >> 6); \
;     const int gw = blockIdx.x * NWAVES + wave, NGW = gridDim.x * NWAVES; (void)lane; (void)gw; (void)NGW
; #define GSYNC(j) do { gbar(2 * (L * 11 + (j))); gbar(2 * (L * 11 + (j)) + 1); } while (0)
; #define GSYNC(j) xbar(lds)
; __device__ __forceinline__ void prologue(const kptr_t kp, LAS float* scr, int gw, int NGW, int lane) {
;     ...
;             if (r < IT_IN) { const int kb = r / 144, nb = r % 144; transpose_item(KPTR(const float, 9) + (size_t)l * D * INC, INC, (bf16_t*)(wl + W_IN), D, 32 * nb, 0, scr, 64 * kb, 32 * nb, lane); continue; } r -= IT_IN;
;             if (r < IT_P) { const int kb = r / 32, nb = r % 32, n0 = 32 * nb; transpose_item(KPTR(const float, 16) + (size_t)l * 512 * D, D, (bf16_t*)(wl + W_PAB), D, 256 * (n0 / 128) + (n0 % 128), 0, scr, 64 * kb, n0, lane); continue; } r -= IT_P;
;             if (r < IT_P) { const int kb = r / 32, nb = r % 32, n0 = 32 * nb; transpose_item(KPTR(const float, 17) + (size_t)l * 512 * D, D, (bf16_t*)(wl + W_PAB), D, 256 * (n0 / 128) + 128 + (n0 % 128), 512, scr, 64 * kb, n0, lane); continue; } r -= IT_P;
;             if (r < IT_O) { const int kb = r / 32, nb = r % 32; transpose_item(KPTR(const float, 18) + (size_t)l * D * D, D, (bf16_t*)(wl + W_O), D, 32 * nb, 0, scr, 64 * kb, 32 * nb, lane); continue; } r -= IT_O;
;             if (r < IT_UP) { const int kb = r / 176, nb = r % 176; transpose_item(KPTR(const float, 19) + (size_t)l * D * 2 * DFF, 2 * DFF, (bf16_t*)(wl + W_UP2), D, up_row(32 * nb), 0, scr, 64 * kb, 32 * nb, lane); continue; } r -= IT_UP;
; template <int L> __device__ __forceinline__ void layer_fwd(cg::grid_group& grid, LAS unsigned char* lds) {
;     ...
;     { PH_BEGIN(); run_gemm(lds, (const bf16_t*)(ws + WS_H), (const bf16_t*)(ws + WL + W_UP2), Mr, 2 * DFF, D, pg8::EpiSwiGLU{(bf16_t*)(ws + WS_G)}); }
;     GSYNC(9);
.LBB0_1270:
	s_cmp_lt_u32 s2, 44
	s_cbranch_scc1 .Lslot_4_skip
	v_writelane_b32 v250, s3, 0
	v_writelane_b32 v250, s4, 1
	v_writelane_b32 v250, s5, 2
	v_writelane_b32 v250, s6, 3
	v_writelane_b32 v250, s7, 4
	v_writelane_b32 v250, s8, 5
	v_writelane_b32 v250, s9, 6
	v_writelane_b32 v250, s10, 7
	v_writelane_b32 v250, s11, 8
	v_writelane_b32 v250, s12, 9
	v_writelane_b32 v250, s13, 10
	v_writelane_b32 v250, s14, 11
	v_writelane_b32 v250, s15, 12
	v_writelane_b32 v250, s16, 13
	v_writelane_b32 v250, s17, 14
	v_writelane_b32 v250, s18, 15
	v_writelane_b32 v250, s19, 16
	v_writelane_b32 v250, s20, 17
	v_writelane_b32 v250, s21, 18
	v_writelane_b32 v250, s22, 19
	v_writelane_b32 v250, s23, 20
	v_writelane_b32 v250, s24, 21
	v_writelane_b32 v250, s25, 22
	v_writelane_b32 v250, s26, 23
	v_writelane_b32 v250, s27, 24
	v_writelane_b32 v250, s28, 25
	v_writelane_b32 v250, s29, 26
	v_writelane_b32 v250, s30, 27
	v_writelane_b32 v250, s31, 28
	v_writelane_b32 v250, s32, 29
	v_writelane_b32 v250, s33, 30
	v_writelane_b32 v250, s34, 31
	v_writelane_b32 v250, s35, 32
	v_writelane_b32 v250, s36, 33
	v_writelane_b32 v250, s37, 34
	v_writelane_b32 v250, s38, 35
	v_writelane_b32 v250, s39, 36
	v_writelane_b32 v250, s40, 37
	v_writelane_b32 v250, s41, 38
	v_writelane_b32 v250, s42, 39
	v_writelane_b32 v250, s43, 40
	v_writelane_b32 v250, s44, 41
	v_writelane_b32 v250, s45, 42
	v_writelane_b32 v250, s46, 43
	v_writelane_b32 v250, s47, 44
	v_writelane_b32 v250, s48, 45
	v_writelane_b32 v250, s49, 46
	v_writelane_b32 v250, s50, 47
	v_writelane_b32 v250, s51, 48
	v_writelane_b32 v250, s52, 49
	v_writelane_b32 v250, s53, 50
	v_writelane_b32 v250, s54, 51
	v_writelane_b32 v250, s55, 52
	v_writelane_b32 v250, s56, 53
	v_writelane_b32 v250, s57, 54
	v_writelane_b32 v250, s58, 55
	v_writelane_b32 v250, s59, 56
	v_writelane_b32 v250, s60, 57
	v_writelane_b32 v250, s61, 58
	v_writelane_b32 v250, s62, 59
	v_writelane_b32 v250, s63, 60
	v_writelane_b32 v250, s64, 61
	v_writelane_b32 v250, s65, 62
	v_writelane_b32 v250, s66, 63
	v_writelane_b32 v251, s67, 0
	v_writelane_b32 v251, s68, 1
	v_writelane_b32 v251, s69, 2
	v_writelane_b32 v251, s70, 3
	v_writelane_b32 v251, s71, 4
	v_writelane_b32 v251, s72, 5
	v_writelane_b32 v251, s73, 6
	v_writelane_b32 v251, s74, 7
	v_writelane_b32 v251, s75, 8
	v_writelane_b32 v251, s76, 9
	v_writelane_b32 v251, s77, 10
	v_writelane_b32 v251, s78, 11
	v_writelane_b32 v251, s79, 12
	v_writelane_b32 v251, s80, 13
	v_writelane_b32 v251, s81, 14
	v_writelane_b32 v251, s82, 15
	v_writelane_b32 v251, s83, 16
	v_writelane_b32 v251, s84, 17
	v_writelane_b32 v251, s85, 18
	v_writelane_b32 v251, s86, 19
	v_writelane_b32 v251, s87, 20
	v_writelane_b32 v251, s88, 21
	v_writelane_b32 v251, s89, 22
	v_writelane_b32 v251, s90, 23
	v_writelane_b32 v251, s91, 24
	v_writelane_b32 v251, s92, 25
	v_writelane_b32 v251, s93, 26
	v_writelane_b32 v251, s94, 27
	v_writelane_b32 v251, s95, 28
	v_writelane_b32 v251, s96, 29
	v_writelane_b32 v251, s97, 30
	v_mov_b32_e32 v236, v200
	v_mov_b32_e32 v237, v201
	v_mov_b32_e32 v238, v202
	v_mov_b32_e32 v239, v203
	v_mov_b32_e32 v240, v204
	v_mov_b32_e32 v241, v205
	v_mov_b32_e32 v242, v206
	v_mov_b32_e32 v243, v207
	v_mov_b32_e32 v244, v208
	v_mov_b32_e32 v245, v209
	v_mov_b32_e32 v246, v210
	v_mov_b32_e32 v247, v211
	s_mov_b32 s98, 0x4a20
	s_mov_b32 s99, 0x6a0
	s_mov_b32 s100, 0x6380
	s_mov_b32 s101, 14
	s_branch .Lcv_hop2

; __device__ __forceinline__ unsigned cvtpk_s(float lo, float hi) { f32x2_t v = {lo, hi}; bf16x2_t b = __builtin_convertvector(v, bf16x2_t); return __builtin_bit_cast(unsigned, b); }
; #define PH_BEGIN() const kptr_t kp = kargs(); unsigned char* const ws = KWS(); (void)ws; int tid_ = threadIdx.x; asm volatile("" : "+v"(tid_)); const int lane = tid_ & 63, wave = __builtin_amdgcn_readfirstlane(tid_ >> 6); \
;     const int gw = blockIdx.x * NWAVES + wave, NGW = gridDim.x * NWAVES; (void)lane; (void)gw; (void)NGW
; #define GSYNC(j) do { gbar(2 * (L * 11 + (j))); gbar(2 * (L * 11 + (j)) + 1); } while (0)
; #define GSYNC(j) xbar(lds)
; __device__ __forceinline__ void prologue(const kptr_t kp, LAS float* scr, int gw, int NGW, int lane) {
;     ...
;             if (r < IT_DN) { const int kb = r / 32, nb = r % 32; transpose_item(KPTR(const float, 20) + (size_t)l * DFF * D, D, (bf16_t*)(wl + W_DN2), DFF, 32 * nb, 0, scr, 64 * kb, 32 * nb, lane); continue; } r -= IT_DN;
;             if (r < IT_Z) {
;                 const int zk0 = ((r & 255) < 128) ? 512 : 0;
;                 *(u32x4*)((bf16_t*)(wl + W_PAB) + (size_t)r * D + zk0 + 8 * lane) = (u32x4){0u, 0u, 0u, 0u}; continue; } r -= IT_Z;
;             {
;                 const float* s = KPTR(const float, 14) + (size_t)l * 65536 + (size_t)(r * 64 + lane) * 8; const f32x4 v0 = *(const f32x4*)s, v1 = *(const f32x4*)(s + 4);
;                 u32x4 o; o.x = cvtpk_s(v0[0], v0[1]); o.y = cvtpk_s(v0[2], v0[3]); o.z = cvtpk_s(v1[0], v1[1]); o.w = cvtpk_s(v1[2], v1[3]);
;                 *(u32x4*)((bf16_t*)(wl + W_S) + (size_t)(r * 64 + lane) * 8) = o; continue; }
; template <int L> __device__ __forceinline__ void layer_fwd(cg::grid_group& grid, LAS unsigned char* lds) {
;     ...
;     { PH_BEGIN(); run_gemm(lds, (const bf16_t*)(ws + WS_H), (const bf16_t*)(ws + WL + W_UP1), MALL, 2 * DFF, D, pg8::EpiSwiGLU{(bf16_t*)(ws + WS_G)}); }
;     GSYNC(1);
.LBB0_1490:
	s_cmp_lt_u32 s2, 44
	s_cbranch_scc1 .Lslot_5_skip
	v_writelane_b32 v250, s3, 0
	v_writelane_b32 v250, s4, 1
	v_writelane_b32 v250, s5, 2
	v_writelane_b32 v250, s6, 3
	v_writelane_b32 v250, s7, 4
	v_writelane_b32 v250, s8, 5
	v_writelane_b32 v250, s9, 6
	v_writelane_b32 v250, s10, 7
	v_writelane_b32 v250, s11, 8
	v_writelane_b32 v250, s12, 9
	v_writelane_b32 v250, s13, 10
	v_writelane_b32 v250, s14, 11
	v_writelane_b32 v250, s15, 12
	v_writelane_b32 v250, s16, 13
	v_writelane_b32 v250, s17, 14
	v_writelane_b32 v250, s18, 15
	v_writelane_b32 v250, s19, 16
	v_writelane_b32 v250, s20, 17
	v_writelane_b32 v250, s21, 18
	v_writelane_b32 v250, s22, 19
	v_writelane_b32 v250, s23, 20
	v_writelane_b32 v250, s24, 21
	v_writelane_b32 v250, s25, 22
	v_writelane_b32 v250, s26, 23
	v_writelane_b32 v250, s27, 24
	v_writelane_b32 v250, s28, 25
	v_writelane_b32 v250, s29, 26
	v_writelane_b32 v250, s30, 27
	v_writelane_b32 v250, s31, 28
	v_writelane_b32 v250, s32, 29
	v_writelane_b32 v250, s33, 30
	v_writelane_b32 v250, s34, 31
	v_writelane_b32 v250, s35, 32
	v_writelane_b32 v250, s36, 33
	v_writelane_b32 v250, s37, 34
	v_writelane_b32 v250, s38, 35
	v_writelane_b32 v250, s39, 36
	v_writelane_b32 v250, s40, 37
	v_writelane_b32 v250, s41, 38
	v_writelane_b32 v250, s42, 39
	v_writelane_b32 v250, s43, 40
	v_writelane_b32 v250, s44, 41
	v_writelane_b32 v250, s45, 42
	v_writelane_b32 v250, s46, 43
	v_writelane_b32 v250, s47, 44
	v_writelane_b32 v250, s48, 45
	v_writelane_b32 v250, s49, 46
	v_writelane_b32 v250, s50, 47
	v_writelane_b32 v250, s51, 48
	v_writelane_b32 v250, s52, 49
	v_writelane_b32 v250, s53, 50
	v_writelane_b32 v250, s54, 51
	v_writelane_b32 v250, s55, 52
	v_writelane_b32 v250, s56, 53
	v_writelane_b32 v250, s57, 54
	v_writelane_b32 v250, s58, 55
	v_writelane_b32 v250, s59, 56
	v_writelane_b32 v250, s60, 57
	v_writelane_b32 v250, s61, 58
	v_writelane_b32 v250, s62, 59
	v_writelane_b32 v250, s63, 60
	v_writelane_b32 v250, s64, 61
	v_writelane_b32 v250, s65, 62
	v_writelane_b32 v250, s66, 63
	v_writelane_b32 v251, s67, 0
	v_writelane_b32 v251, s68, 1
	v_writelane_b32 v251, s69, 2
	v_writelane_b32 v251, s70, 3
	v_writelane_b32 v251, s71, 4
	v_writelane_b32 v251, s72, 5
	v_writelane_b32 v251, s73, 6
	v_writelane_b32 v251, s74, 7
	v_writelane_b32 v251, s75, 8
	v_writelane_b32 v251, s76, 9
	v_writelane_b32 v251, s77, 10
	v_writelane_b32 v251, s78, 11
	v_writelane_b32 v251, s79, 12
	v_writelane_b32 v251, s80, 13
	v_writelane_b32 v251, s81, 14
	v_writelane_b32 v251, s82, 15
	v_writelane_b32 v251, s83, 16
	v_writelane_b32 v251, s84, 17
	v_writelane_b32 v251, s85, 18
	v_writelane_b32 v251, s86, 19
	v_writelane_b32 v251, s87, 20
	v_writelane_b32 v251, s88, 21
	v_writelane_b32 v251, s89, 22
	v_writelane_b32 v251, s90, 23
	v_writelane_b32 v251, s91, 24
	v_writelane_b32 v251, s92, 25
	v_writelane_b32 v251, s93, 26
	v_writelane_b32 v251, s94, 27
	v_writelane_b32 v251, s95, 28
	v_writelane_b32 v251, s96, 29
	v_writelane_b32 v251, s97, 30
	v_mov_b32_e32 v236, v200
	v_mov_b32_e32 v237, v201
	v_mov_b32_e32 v238, v202
	v_mov_b32_e32 v239, v203
	v_mov_b32_e32 v240, v204
	v_mov_b32_e32 v241, v205
	v_mov_b32_e32 v242, v206
	v_mov_b32_e32 v243, v207
	v_mov_b32_e32 v244, v208
	v_mov_b32_e32 v245, v209
	v_mov_b32_e32 v246, v210
	v_mov_b32_e32 v247, v211
	s_mov_b32 s98, 0x6220
	s_mov_b32 s99, 0x6a0
	s_mov_b32 s100, 0x7180
	s_mov_b32 s101, 15
	s_branch .Lcv_hop3
